# H1: next-item tile prefetch issued at top of iteration into spare registers
# speedup vs baseline: 1.0196x; 1.0007x over previous
; #define H1_PREFETCH(itn) do { const int n_ = (itn) >> 4, h_ = (itn) & 15; const h16* base_ = P.PA + (size_t)(n_ * CH) * 8192 + h_ * HD; \
;         tile_ld(base_ + HW, pf, tid); tile_ld(base_ + 2 * HW, pv, tid); } while (0)
; __device__ __forceinline__ void h1_phase(const Ptrs& P, LAS unsigned char* lds, int bx, int G, int tid) {
;     ...
;     const int d = tid & 127, i = __builtin_amdgcn_readfirstlane(tid >> 7), lane = tid & 63, w = __builtin_amdgcn_readfirstlane(tid >> 6);
;     const int fr = lane & 15, fq = lane >> 4;
;     const int NIT = NCH * NH;
;     if (bx >= NIT) return;
;     h16x8 pf[2], pv[2];
;     ...
;     H1_PREFETCH(bx);
;     const bool hfix = (G & 15) == 0;
;     float l0 = P.lb_logits[(bx & 15) * HD + d], l1 = P.lb_logits[HW + (bx & 15) * HD + d];
;     int itprev = -1;
;     for (int it = bx; it < NIT; it += G) {
.LBB0_217:
	s_or_b64 exec, exec, s[0:1]
	s_cmpk_lt_i32 s2, 0x800
	s_cselect_b64 s[4:5], -1, 0
	s_and_b32 s0, s30, 15
	s_cmp_lg_u32 s0, 0
	s_cselect_b64 s[42:43], -1, 0
	s_add_i32 s0, 0, 0x24018
	s_waitcnt lgkmcnt(0)
	v_mov_b32_e32 v0, s0
	s_add_i32 s0, 0, 0x24028
	v_mov_b32_e32 v2, s0
	s_add_i32 s0, 0, 0x24060
	v_mov_b32_e32 v4, s0
	s_barrier
	ds_read_b64 v[0:1], v0
	ds_read_b64 v[2:3], v2
	ds_read_b64 v[4:5], v4
	v_mbcnt_lo_u32_b32 v17, -1, 0
	v_mbcnt_hi_u32_b32 v17, -1, v17
	s_mov_b32 s9, 0
	v_or_b32_e32 v24, s33, v17
	s_waitcnt lgkmcnt(2)
	v_readfirstlane_b32 s11, v1
	v_readfirstlane_b32 s10, v0
	s_waitcnt lgkmcnt(1)
	v_readfirstlane_b32 s1, v3
	v_readfirstlane_b32 s0, v2
	s_waitcnt lgkmcnt(0)
	v_readfirstlane_b32 s7, v5
	v_readfirstlane_b32 s28, v4
	v_readfirstlane_b32 s8, v24
	s_and_b64 vcc, exec, s[4:5]
	s_cbranch_vccz .LBB0_234
	s_add_u32 s27, s28, 0x14200000
	s_addc_u32 s45, s7, 0
	s_add_u32 s29, s28, 0x2c200000
	s_addc_u32 s44, s7, 0
	s_add_u32 s26, s28, 0x100000
	s_addc_u32 s48, s7, 0
	s_lshl_b32 s12, s2, 2
	s_andn2_b32 s12, s12, 63
	s_lshl_b32 s46, s2, 7
	s_ashr_i32 s13, s12, 31
	s_and_b32 s16, s46, 0x780
	s_lshl_b64 s[12:13], s[12:13], 14
	s_ashr_i32 s22, s8, 7
	s_add_u32 s12, s27, s12
	s_addc_u32 s13, s45, s13
	s_lshl_b32 s14, s16, 1
	v_lshlrev_b32_e32 v16, 3, v24
	s_add_u32 s12, s12, s14
	v_and_b32_e32 v32, 0x78, v16
	v_add_u32_e32 v6, 0x200, v24
	s_addc_u32 s13, s13, 0
	v_mov_b32_e32 v19, 0
	v_lshlrev_b32_e32 v18, 1, v32
	v_ashrrev_i32_e32 v26, 4, v24
	v_ashrrev_i32_e32 v28, 4, v6
	v_lshl_add_u64 v[0:1], s[12:13], 0, v[18:19]
	s_mov_b64 s[12:13], 0x1000
	v_ashrrev_i32_e32 v27, 31, v26
	v_ashrrev_i32_e32 v29, 31, v28
	s_mov_b64 s[14:15], 0x2000
	v_and_b32_e32 v34, 0x7f, v24
	v_lshl_add_u64 v[2:3], v[0:1], 0, s[12:13]
	v_lshlrev_b64 v[20:21], 14, v[26:27]
	v_lshlrev_b64 v[22:23], 14, v[28:29]
	v_lshl_add_u64 v[0:1], v[0:1], 0, s[14:15]
	v_lshl_add_u64 v[4:5], v[2:3], 0, v[20:21]
	v_lshl_add_u64 v[2:3], v[2:3], 0, v[22:23]
	v_lshl_add_u64 v[30:31], v[0:1], 0, v[20:21]
	v_or_b32_e32 v25, s16, v34
	global_load_dwordx4 v[232:235], v[4:5], off
	global_load_dwordx4 v[236:239], v[2:3], off
	v_lshl_add_u64 v[36:37], v[0:1], 0, v[22:23]
	global_load_dwordx4 v[240:243], v[30:31], off
	global_load_dwordx4 v[244:247], v[36:37], off
	v_lshlrev_b32_e32 v30, 2, v25
	v_mov_b32_e32 v31, v19
	v_lshl_add_u64 v[36:37], s[10:11], 0, v[30:31]
	s_movk_i32 s16, 0x2000
	v_add_co_u32_e32 v38, vcc, s16, v36
	v_lshlrev_b32_e32 v25, 1, v34
	s_nop 0
	v_addc_co_u32_e32 v39, vcc, 0, v37, vcc
	global_load_dword v37, v30, s[10:11]
	global_load_dword v40, v[38:39], off
	v_add_u32_e32 v35, 0, v25
	v_lshlrev_b32_e32 v24, 4, v24
	v_add_u32_e32 v36, v35, v25
	v_and_b32_e32 v25, 0xffffff00, v24
	s_lshl_b32 s47, s22, 12
	s_and_b32 s16, s8, 0x3fffff80
	s_lshl_b32 s51, s22, 5
	v_add3_u32 v38, 0, v18, v25
	v_bitop3_b32 v18, v16, v26, 56 bitop3:0x6c
	s_cmpk_lt_u32 s8, 0x80
	v_lshl_add_u32 v33, v18, 1, 0
	v_bitop3_b32 v18, v28, v16, 56 bitop3:0x78
	v_lshl_add_u32 v41, s16, 2, v36
	s_cselect_b64 s[16:17], -1, 0
	s_ashr_i32 s8, s8, 2
	v_bfe_u32 v31, v17, 4, 2
	s_movk_i32 s18, 0x90
	v_lshl_add_u32 v47, v18, 1, 0
	v_bfi_b32 v18, -16, s8, v17
	v_and_b32_e32 v30, 15, v17
	v_lshlrev_b32_e32 v44, 3, v31
	v_mul_lo_u32 v17, v18, s18
	s_and_b32 s24, s8, -16
	v_add_u32_e32 v45, 0, v17
	v_lshl_add_u32 v50, v30, 1, 0
	v_mul_u32_u24_e32 v51, 0x90, v30
	v_bitop3_b32 v30, v18, v44, 56 bitop3:0x6c
	s_cmp_lt_i32 s22, 1
	v_lshl_add_u32 v43, v30, 1, v45
	v_or_b32_e32 v30, 32, v44
	v_mad_u32_u24 v48, v34, s18, 0
	s_cselect_b64 s[18:19], -1, 0
	s_cmp_lt_i32 s22, 2
	v_bitop3_b32 v18, v18, v30, 56 bitop3:0x6c
	s_cselect_b64 s[20:21], -1, 0
	s_cmp_lt_i32 s22, 3
	v_lshl_add_u32 v44, v18, 1, v45
	v_lshlrev_b32_e32 v18, 10, v31
	s_cselect_b64 s[22:23], -1, 0
	v_lshl_or_b32 v52, s24, 8, v18
	s_lshl_b64 s[24:25], s[2:3], 9
	s_add_u32 s24, s26, s24
	v_mul_u32_u24_e32 v46, 0x90, v32
	v_lshl_add_u32 v49, v31, 4, 0
	v_add_u32_e32 v42, 0, v24
	v_add_u32_e32 v26, 0x1000, v16
	v_add_u32_e32 v24, 0x2000, v16
	v_add_u32_e32 v28, 0x3000, v16
	v_lshlrev_b32_e32 v18, 2, v34
	s_addc_u32 s25, s48, s25
	v_add_u32_e32 v39, 0xd800, v42
	v_ashrrev_i32_e32 v17, 31, v16
	v_ashrrev_i32_e32 v27, 31, v26
	v_ashrrev_i32_e32 v25, 31, v24
	v_ashrrev_i32_e32 v29, 31, v28
	v_lshl_add_u64 v[30:31], s[24:25], 0, v[18:19]
	s_lshl_b64 s[24:25], s[30:31], 9
	s_lshl_b32 s48, s30, 7
	s_mov_b32 s8, -1
	v_add_u32_e32 v45, v33, v46
	v_add_u32_e32 v46, v47, v46
	s_movk_i32 s49, 0x7fff
	s_mov_b32 s50, 0xffff0000
	v_add_u32_e32 v47, s51, v48
	v_lshlrev_b32_e32 v18, 1, v32
	v_add_u32_e32 v48, v49, v51
	v_add_u32_e32 v49, v50, v52
	s_mov_b32 s26, s2
	s_andn2_b64 vcc, exec, s[42:43]
	s_cbranch_vccz .LBB0_220
	s_branch .LBB0_221

; #define LAS __attribute__((address_space(3)))
; __device__ __forceinline__ unsigned short bf1(float x) { unsigned r; asm("v_cvt_pk_bf16_f32 %0, %1, %1" : "=v"(r) : "v"(x)); return (unsigned short)r; }
; __device__ __forceinline__ void tile_st(LAS h16* dst, const h16x8 (&r)[2], int tid) {
; #pragma unroll
;     for (int rep = 0; rep < 2; ++rep) { const int cidx = tid + 512 * rep; *(LAS h16x8*)(dst + (cidx >> 4) * 128 + (cidx & 15) * 8) = r[rep]; }
; }
; __device__ __forceinline__ void vt_st(LAS unsigned short* VT, const h16x8 (&r)[2], int tid) {
; #pragma unroll
;     for (int rep = 0; rep < 2; ++rep) { const int cidx = tid + 512 * rep, sI = cidx >> 4, ec = (cidx & 15) * 8;
; #pragma unroll
;         for (int x = 0; x < 8; ++x) VT[vt_idx(ec + x, sI)] = bf1((float)r[rep][x]); }
; }
.LBB0_221:
	s_waitcnt vmcnt(1)
	v_mov_b32_e32 v8, v232
	v_mov_b32_e32 v9, v233
	v_mov_b32_e32 v10, v234
	v_mov_b32_e32 v11, v235
	v_mov_b32_e32 v12, v236
	v_mov_b32_e32 v13, v237
	v_mov_b32_e32 v14, v238
	v_mov_b32_e32 v15, v239
	v_mov_b32_e32 v4, v240
	v_mov_b32_e32 v5, v241
	v_mov_b32_e32 v6, v242
	v_mov_b32_e32 v7, v243
	v_cvt_f32_f16_e32 v32, v4
	v_cvt_f32_f16_sdwa v4, v4 dst_sel:DWORD dst_unused:UNUSED_PAD src0_sel:WORD_1
	ds_write_b128 v38, v[8:11] offset:38912
	ds_write_b128 v38, v[12:15] offset:47104
	v_cvt_pk_bf16_f32 v8, v32, v32
	v_cvt_pk_bf16_f32 v4, v4, v4
	ds_write_b16 v45, v8 offset:18432
	v_cvt_f32_f16_e32 v8, v5
	ds_write_b16 v45, v4 offset:18576
	v_cvt_f32_f16_sdwa v4, v5 dst_sel:DWORD dst_unused:UNUSED_PAD src0_sel:WORD_1
	v_cvt_pk_bf16_f32 v5, v8, v8
	ds_write_b16 v45, v5 offset:18720
	v_cvt_f32_f16_e32 v5, v6
	v_cvt_pk_bf16_f32 v4, v4, v4
	v_cvt_pk_bf16_f32 v5, v5, v5
	ds_write_b16 v45, v4 offset:18864
	v_cvt_f32_f16_sdwa v4, v6 dst_sel:DWORD dst_unused:UNUSED_PAD src0_sel:WORD_1
	ds_write_b16 v45, v5 offset:19008
	v_cvt_f32_f16_e32 v5, v7
	v_cvt_pk_bf16_f32 v4, v4, v4
	v_cvt_pk_bf16_f32 v5, v5, v5
	ds_write_b16 v45, v4 offset:19152
	v_cvt_f32_f16_sdwa v4, v7 dst_sel:DWORD dst_unused:UNUSED_PAD src0_sel:WORD_1
	ds_write_b16 v45, v5 offset:19296
	s_waitcnt vmcnt(0)
	v_mov_b32_e32 v0, v244
	v_mov_b32_e32 v1, v245
	v_mov_b32_e32 v2, v246
	v_mov_b32_e32 v3, v247
	s_add_i32 s90, s26, s30
	s_cmpk_lt_i32 s90, 0x800
	s_cselect_b32 s90, s90, s26
	s_lshl_b32 s91, s90, 2
	s_and_b32 s92, s91, 0xffffffc0
	s_ashr_i32 s93, s92, 31
	s_lshl_b64 s[92:93], s[92:93], 14
	s_add_u32 s91, s27, s92
	s_addc_u32 s93, s45, s93
	s_lshl_b32 s90, s90, 8
	s_and_b32 s90, s90, 0xf00
	s_add_u32 s92, s91, s90
	s_addc_u32 s93, s93, 0
	v_lshl_add_u64 v[248:249], s[92:93], 0, v[18:19]
	v_lshl_add_u64 v[250:251], v[248:249], 0, s[12:13]
	v_lshl_add_u64 v[252:253], v[250:251], 0, v[20:21]
	v_lshl_add_u64 v[250:251], v[250:251], 0, v[22:23]
	v_lshl_add_u64 v[248:249], v[248:249], 0, s[14:15]
	global_load_dwordx4 v[232:235], v[252:253], off
	global_load_dwordx4 v[236:239], v[250:251], off
	v_lshl_add_u64 v[250:251], v[248:249], 0, v[20:21]
	v_lshl_add_u64 v[248:249], v[248:249], 0, v[22:23]
	global_load_dwordx4 v[240:243], v[250:251], off
	global_load_dwordx4 v[244:247], v[248:249], off
	v_cvt_f32_f16_e32 v5, v0
	v_cvt_f32_f16_sdwa v0, v0 dst_sel:DWORD dst_unused:UNUSED_PAD src0_sel:WORD_1
	v_cvt_pk_bf16_f32 v4, v4, v4
	v_cvt_pk_bf16_f32 v0, v0, v0
	ds_write_b16 v45, v4 offset:19440
	v_cvt_pk_bf16_f32 v4, v5, v5
	ds_write_b16 v46, v0 offset:18576
	v_cvt_f32_f16_sdwa v0, v1 dst_sel:DWORD dst_unused:UNUSED_PAD src0_sel:WORD_1
	ds_write_b16 v46, v4 offset:18432
	v_cvt_f32_f16_e32 v4, v1
	v_cvt_pk_bf16_f32 v1, v4, v4
	v_cvt_pk_bf16_f32 v0, v0, v0
	ds_write_b16 v46, v1 offset:18720
	v_cvt_f32_f16_e32 v1, v2
	ds_write_b16 v46, v0 offset:18864
	v_cvt_f32_f16_sdwa v0, v2 dst_sel:DWORD dst_unused:UNUSED_PAD src0_sel:WORD_1
	v_cvt_pk_bf16_f32 v1, v1, v1
	v_cvt_pk_bf16_f32 v0, v0, v0
	ds_write_b16 v46, v1 offset:19008
	v_cvt_f32_f16_e32 v1, v3
	ds_write_b16 v46, v0 offset:19152
	v_cvt_pk_bf16_f32 v0, v1, v1
	v_cvt_f32_f16_sdwa v2, v3 dst_sel:DWORD dst_unused:UNUSED_PAD src0_sel:WORD_1
	ds_write_b16 v46, v0 offset:19296
	v_cvt_pk_bf16_f32 v0, v2, v2
	v_add_u32_e32 v10, s47, v35
	ds_write_b16 v46, v0 offset:19440
	s_waitcnt lgkmcnt(0)
	s_barrier
; __device__ __forceinline__ void h1_phase(const Ptrs& P, LAS unsigned char* lds, int bx, int G, int tid) {
;     ...
;         const float oml = 1.f - __builtin_amdgcn_rcpf(1.f + __expf(l1 - l0));
;         float kk[16], pc[16], run = 1.f;
; #pragma unroll
;         for (int u = 0; u < 16; ++u) { const float xv = (float)FST[(16 * i + u) * 128 + d]; const float k = oml * __builtin_amdgcn_rcpf(1.f + __expf(xv)); run *= (1.f - k); kk[u] = k; pc[u] = run; }
;         tot[i * 128 + d] = run;
;         __syncthreads();
	ds_read_u16 v0, v10 offset:38912
	ds_read_u16 v1, v10 offset:39168
	ds_read_u16 v2, v10 offset:39424
	ds_read_u16 v3, v10 offset:39680
	ds_read_u16 v6, v10 offset:39936
	ds_read_u16 v7, v10 offset:40192
	ds_read_u16 v11, v10 offset:40448
	ds_read_u16 v12, v10 offset:40704
	s_waitcnt lgkmcnt(6)
	v_cvt_f32_f16_e32 v1, v1
	v_cvt_f32_f16_e32 v0, v0
	s_waitcnt lgkmcnt(5)
	v_cvt_f32_f16_e32 v2, v2
	s_waitcnt lgkmcnt(4)
	v_cvt_f32_f16_e32 v3, v3
	s_waitcnt vmcnt(0)
	v_sub_f32_e32 v4, v40, v37
	v_mul_f32_e32 v4, 0x3fb8aa3b, v4
	v_mul_f32_e32 v1, 0x3fb8aa3b, v1
	v_exp_f32_e32 v4, v4
	v_mul_f32_e32 v0, 0x3fb8aa3b, v0
	v_exp_f32_e32 v1, v1
	v_mul_f32_e32 v2, 0x3fb8aa3b, v2
	v_mul_f32_e32 v3, 0x3fb8aa3b, v3
	v_exp_f32_e32 v0, v0
	v_exp_f32_e32 v2, v2
	v_exp_f32_e32 v3, v3
	v_add_f32_e32 v4, 1.0, v4
	v_add_f32_e32 v1, 1.0, v1
	v_rcp_f32_e32 v8, v4
	v_add_f32_e32 v0, 1.0, v0
	v_rcp_f32_e32 v4, v1
	v_add_f32_e32 v1, 1.0, v2
	v_add_f32_e32 v2, 1.0, v3
	v_rcp_f32_e32 v0, v0
	v_rcp_f32_e32 v1, v1
	v_rcp_f32_e32 v5, v2
	v_sub_f32_e32 v8, 1.0, v8
	s_andn2_b64 vcc, exec, s[18:19]
	v_pk_mul_f32 v[2:3], v[8:9], v[0:1] op_sel_hi:[0,1]
	v_pk_mul_f32 v[0:1], v[8:9], v[4:5] op_sel_hi:[0,1]
	s_waitcnt lgkmcnt(3)
	v_cvt_f32_f16_e32 v5, v6
	v_sub_f32_e32 v50, 1.0, v2
	v_sub_f32_e32 v4, 1.0, v0
	v_mul_f32_e32 v51, v50, v4
	v_sub_f32_e32 v4, 1.0, v3
	v_mul_f32_e32 v9, v51, v4
	v_mul_f32_e32 v4, 0x3fb8aa3b, v5
	v_sub_f32_e32 v5, 1.0, v1
	v_mul_f32_e32 v52, v9, v5
	s_waitcnt lgkmcnt(2)
	v_cvt_f32_f16_e32 v5, v7
	s_waitcnt lgkmcnt(1)
	v_cvt_f32_f16_e32 v6, v11
	s_waitcnt lgkmcnt(0)
	v_cvt_f32_f16_e32 v7, v12
	v_exp_f32_e32 v4, v4
	v_mul_f32_e32 v5, 0x3fb8aa3b, v5
	v_exp_f32_e32 v5, v5
	v_mul_f32_e32 v6, 0x3fb8aa3b, v6
	v_exp_f32_e32 v6, v6
	v_add_f32_e32 v4, 1.0, v4
	v_add_f32_e32 v11, 1.0, v5
	v_mul_f32_e32 v5, 0x3fb8aa3b, v7
	v_exp_f32_e32 v7, v5
	v_add_f32_e32 v5, 1.0, v6
	v_rcp_f32_e32 v4, v4
	v_rcp_f32_e32 v5, v5
	v_add_f32_e32 v7, 1.0, v7
	v_rcp_f32_e32 v6, v11
	v_rcp_f32_e32 v7, v7
	v_pk_mul_f32 v[4:5], v[8:9], v[4:5] op_sel_hi:[0,1]
	v_sub_f32_e32 v11, 1.0, v4
	v_mul_f32_e32 v53, v52, v11
	v_pk_mul_f32 v[6:7], v[8:9], v[6:7] op_sel_hi:[0,1]
	v_sub_f32_e32 v11, 1.0, v6
	v_mul_f32_e32 v55, v53, v11
	v_sub_f32_e32 v11, 1.0, v5
	v_mul_f32_e32 v54, v55, v11
	v_sub_f32_e32 v11, 1.0, v7
	ds_read_u16 v12, v10 offset:40960
	ds_read_u16 v13, v10 offset:41216
	ds_read_u16 v14, v10 offset:41472
	ds_read_u16 v15, v10 offset:41728
	ds_read_u16 v32, v10 offset:41984
	ds_read_u16 v33, v10 offset:42240
	ds_read_u16 v61, v10 offset:42496
	ds_read_u16 v62, v10 offset:42752
	v_mul_f32_e32 v56, v54, v11
	s_waitcnt lgkmcnt(6)
	v_cvt_f32_f16_e32 v11, v13
	v_cvt_f32_f16_e32 v10, v12
	s_waitcnt lgkmcnt(5)
	v_cvt_f32_f16_e32 v12, v14
	s_waitcnt lgkmcnt(4)
	v_cvt_f32_f16_e32 v13, v15
	v_mul_f32_e32 v11, 0x3fb8aa3b, v11
	v_exp_f32_e32 v11, v11
	v_mul_f32_e32 v10, 0x3fb8aa3b, v10
	v_mul_f32_e32 v12, 0x3fb8aa3b, v12
	v_exp_f32_e32 v10, v10
	v_exp_f32_e32 v12, v12
	v_add_f32_e32 v14, 1.0, v11
	v_mul_f32_e32 v11, 0x3fb8aa3b, v13
	v_exp_f32_e32 v13, v11
	v_add_f32_e32 v10, 1.0, v10
	v_add_f32_e32 v11, 1.0, v12
	v_rcp_f32_e32 v10, v10
	v_rcp_f32_e32 v11, v11
	v_add_f32_e32 v12, 1.0, v13
	v_rcp_f32_e32 v14, v14
	v_rcp_f32_e32 v15, v12
	v_pk_mul_f32 v[12:13], v[8:9], v[10:11] op_sel_hi:[0,1]
	v_sub_f32_e32 v10, 1.0, v12
	v_mul_f32_e32 v57, v56, v10
	v_pk_mul_f32 v[10:11], v[8:9], v[14:15] op_sel_hi:[0,1]
	s_waitcnt lgkmcnt(3)
	v_cvt_f32_f16_e32 v15, v32
	v_sub_f32_e32 v14, 1.0, v10
	v_mul_f32_e32 v58, v57, v14
	v_sub_f32_e32 v14, 1.0, v13
	v_mul_f32_e32 v59, v58, v14
	v_mul_f32_e32 v14, 0x3fb8aa3b, v15
	v_sub_f32_e32 v15, 1.0, v11
	v_mul_f32_e32 v60, v59, v15
	s_waitcnt lgkmcnt(2)
	v_cvt_f32_f16_e32 v15, v33
	s_waitcnt lgkmcnt(1)
	v_cvt_f32_f16_e32 v32, v61
	s_waitcnt lgkmcnt(0)
	v_cvt_f32_f16_e32 v33, v62
	v_exp_f32_e32 v14, v14
	v_mul_f32_e32 v15, 0x3fb8aa3b, v15
	v_exp_f32_e32 v15, v15
	v_mul_f32_e32 v32, 0x3fb8aa3b, v32
	v_exp_f32_e32 v32, v32
	v_add_f32_e32 v14, 1.0, v14
	v_add_f32_e32 v61, 1.0, v15
	v_mul_f32_e32 v15, 0x3fb8aa3b, v33
	v_exp_f32_e32 v33, v15
	v_add_f32_e32 v15, 1.0, v32
	v_rcp_f32_e32 v14, v14
	v_rcp_f32_e32 v15, v15
	v_add_f32_e32 v33, 1.0, v33
	v_rcp_f32_e32 v32, v61
	v_rcp_f32_e32 v33, v33
	v_pk_mul_f32 v[14:15], v[8:9], v[14:15] op_sel_hi:[0,1]
	v_sub_f32_e32 v61, 1.0, v14
	v_mul_f32_e32 v61, v60, v61
	v_pk_mul_f32 v[32:33], v[8:9], v[32:33] op_sel_hi:[0,1]
	v_sub_f32_e32 v8, 1.0, v32
	v_mul_f32_e32 v62, v61, v8
	v_sub_f32_e32 v8, 1.0, v15
	v_mul_f32_e32 v63, v62, v8
	v_sub_f32_e32 v8, 1.0, v33
	v_mul_f32_e32 v64, v63, v8
	v_mov_b32_e32 v8, v64
	ds_write_b32 v41, v64 offset:36864
	s_waitcnt lgkmcnt(0)
	s_barrier
	s_cbranch_vccz .LBB0_224
	s_andn2_b64 vcc, exec, s[20:21]
	s_cbranch_vccnz .LBB0_225

; #define LAS __attribute__((address_space(3)))
; #define H1_PREFETCH(itn) do { const int n_ = (itn) >> 4, h_ = (itn) & 15; const h16* base_ = P.PA + (size_t)(n_ * CH) * 8192 + h_ * HD; \
;         tile_ld(base_ + HW, pf, tid); tile_ld(base_ + 2 * HW, pv, tid); } while (0)
; #define H1_FLUSH(itp) do { h16* Lp_ = P.L + (size_t)(itp) * (HD * HD); \
;         _Pragma("unroll") for (int rep = 0; rep < 4; ++rep) { const int cidx = tid + 512 * rep; *(h16x8*)(Lp_ + cidx * 8) = *(const LAS h16x8*)(LT + cidx * 8); } } while (0)
; __device__ __forceinline__ void h1_phase(const Ptrs& P, LAS unsigned char* lds, int bx, int G, int tid) {
;     ...
;         { const int nit = it + G; H1_PREFETCH(nit < NIT ? nit : it); }
;         __syncthreads();
;         f32x4 acc[8];
; #pragma unroll
;         for (int nn = 0; nn < 8; ++nn) acc[nn] = (f32x4){0.f, 0.f, 0.f, 0.f};
; #pragma unroll
;         for (int k2 = 0; k2 < 2; ++k2) {
;             const bf16x8 a = *(const LAS bf16x8*)(VT + vt_idx(16 * w + fr, 32 * k2 + 8 * fq));
; #pragma unroll
;             for (int nn = 0; nn < 8; ++nn) { const bf16x8 b = *(const LAS bf16x8*)(KT + (16 * nn + fr) * 72 + 32 * k2 + 8 * fq);
;                 acc[nn] = __builtin_amdgcn_mfma_f32_16x16x32_bf16(a, b, acc[nn], 0, 0, 0); }
;         }
; #pragma unroll
;         for (int nn = 0; nn < 8; ++nn)
; #pragma unroll
;             for (int j = 0; j < 4; ++j) LT[(16 * w + 4 * fq + j) * HD + 16 * nn + fr] = (h16)acc[nn][j];
;         itprev = it;
;         __syncthreads();
;     }
;     if (itprev >= 0) H1_FLUSH(itprev);
.LBB0_231:
	s_add_i32 s51, s26, s30
	s_cmpk_lt_i32 s51, 0x800
	s_cselect_b32 s8, s51, s26
	s_lshl_b32 s53, s8, 2
	s_and_b32 s54, s53, 0xffffffc0
	s_ashr_i32 s55, s54, 31
	s_lshl_b64 s[54:55], s[54:55], 14
	s_add_u32 s53, s27, s54
	s_addc_u32 s55, s45, s55
	s_lshl_b32 s8, s8, 8
	s_and_b32 s8, s8, 0xf00
	s_add_u32 s54, s53, s8
	s_addc_u32 s55, s55, 0
	s_waitcnt lgkmcnt(0)
	s_barrier
	ds_read_b128 v[50:53], v43 offset:18432
	ds_read_b128 v[54:57], v48
	ds_read_b128 v[58:61], v44 offset:18432
	ds_read_b128 v[62:65], v48 offset:64
	s_waitcnt lgkmcnt(2)
	v_mfma_f32_16x16x32_bf16 v[54:57], v[50:53], v[54:57], 0
	ds_read_b128 v[66:69], v48 offset:2304
	ds_read_b128 v[70:73], v48 offset:2368
	ds_read_b128 v[74:77], v48 offset:4608
	ds_read_b128 v[78:81], v48 offset:4672
	ds_read_b128 v[82:85], v48 offset:6912
	ds_read_b128 v[86:89], v48 offset:6976
	s_waitcnt lgkmcnt(5)
	v_mfma_f32_16x16x32_bf16 v[66:69], v[50:53], v[66:69], 0
	ds_read_b128 v[90:93], v48 offset:9216
	ds_read_b128 v[94:97], v48 offset:9280
	ds_read_b128 v[98:101], v48 offset:11520
	ds_read_b128 v[102:105], v48 offset:11584
	ds_read_b128 v[106:109], v48 offset:13824
	ds_read_b128 v[110:113], v48 offset:13888
	v_mfma_f32_16x16x32_bf16 v[54:57], v[58:61], v[62:65], v[54:57]
	ds_read_b128 v[114:117], v48 offset:16128
	ds_read_b128 v[118:121], v48 offset:16192
	s_add_i32 s46, s46, s48
	s_cmpk_gt_i32 s51, 0x7ff
	s_waitcnt lgkmcnt(11)
	v_mfma_f32_16x16x32_bf16 v[74:77], v[50:53], v[74:77], 0
	s_nop 1
	v_cvt_f16_f32_e32 v32, v54
	v_cvt_f16_f32_e32 v33, v55
	v_cvt_f16_f32_e32 v54, v56
	v_mfma_f32_16x16x32_bf16 v[62:65], v[58:61], v[70:73], v[66:69]
	v_cvt_f16_f32_e32 v55, v57
	ds_write_b16 v49, v32 offset:55296
	ds_write_b16 v49, v33 offset:55552
	ds_write_b16 v49, v54 offset:55808
	ds_write_b16 v49, v55 offset:56064
	v_lshl_add_u64 v[30:31], v[30:31], 0, s[24:25]
	s_waitcnt lgkmcnt(13)
	v_mfma_f32_16x16x32_bf16 v[82:85], v[50:53], v[82:85], 0
	v_cvt_f16_f32_e32 v32, v62
	v_cvt_f16_f32_e32 v33, v63
	v_cvt_f16_f32_e32 v54, v64
	v_mfma_f32_16x16x32_bf16 v[66:69], v[58:61], v[78:81], v[74:77]
	v_cvt_f16_f32_e32 v55, v65
	ds_write_b16 v49, v32 offset:55328
	ds_write_b16 v49, v33 offset:55584
	ds_write_b16 v49, v54 offset:55840
	ds_write_b16 v49, v55 offset:56096
	s_nop 2
	v_cvt_f16_f32_e32 v32, v66
	s_waitcnt lgkmcnt(14)
	v_mfma_f32_16x16x32_bf16 v[90:93], v[50:53], v[90:93], 0
	v_cvt_f16_f32_e32 v33, v67
	v_cvt_f16_f32_e32 v54, v68
	v_cvt_f16_f32_e32 v55, v69
	v_mfma_f32_16x16x32_bf16 v[70:73], v[58:61], v[86:89], v[82:85]
	ds_write_b16 v49, v32 offset:55360
	ds_write_b16 v49, v33 offset:55616
	ds_write_b16 v49, v54 offset:55872
	ds_write_b16 v49, v55 offset:56128
	s_waitcnt lgkmcnt(14)
	v_mfma_f32_16x16x32_bf16 v[98:101], v[50:53], v[98:101], 0
	s_nop 1
	v_cvt_f16_f32_e32 v32, v70
	v_cvt_f16_f32_e32 v33, v71
	v_cvt_f16_f32_e32 v54, v72
	v_mfma_f32_16x16x32_bf16 v[74:77], v[58:61], v[94:97], v[90:93]
	v_cvt_f16_f32_e32 v55, v73
	ds_write_b16 v49, v32 offset:55392
	ds_write_b16 v49, v33 offset:55648
	ds_write_b16 v49, v54 offset:55904
	ds_write_b16 v49, v55 offset:56160
	s_nop 2
	v_cvt_f16_f32_e32 v32, v74
	v_mfma_f32_16x16x32_bf16 v[106:109], v[50:53], v[106:109], 0
	v_cvt_f16_f32_e32 v33, v75
	v_cvt_f16_f32_e32 v54, v76
	v_cvt_f16_f32_e32 v55, v77
	v_mfma_f32_16x16x32_bf16 v[78:81], v[58:61], v[102:105], v[98:101]
	ds_write_b16 v49, v32 offset:55424
	ds_write_b16 v49, v33 offset:55680
	ds_write_b16 v49, v54 offset:55936
	ds_write_b16 v49, v55 offset:56192
	s_waitcnt lgkmcnt(14)
	v_mfma_f32_16x16x32_bf16 v[50:53], v[50:53], v[114:117], 0
	s_nop 1
	v_cvt_f16_f32_e32 v32, v78
	v_cvt_f16_f32_e32 v33, v79
	v_cvt_f16_f32_e32 v54, v80
	v_mfma_f32_16x16x32_bf16 v[82:85], v[58:61], v[110:113], v[106:109]
	v_cvt_f16_f32_e32 v55, v81
	ds_write_b16 v49, v32 offset:55456
	ds_write_b16 v49, v33 offset:55712
	ds_write_b16 v49, v54 offset:55968
	ds_write_b16 v49, v55 offset:56224
	s_nop 2
	v_cvt_f16_f32_e32 v32, v82
	v_mfma_f32_16x16x32_bf16 v[50:53], v[58:61], v[118:121], v[50:53]
	v_cvt_f16_f32_e32 v33, v83
	v_cvt_f16_f32_e32 v54, v84
	v_cvt_f16_f32_e32 v55, v85
	ds_write_b16 v49, v32 offset:55488
	ds_write_b16 v49, v33 offset:55744
	ds_write_b16 v49, v54 offset:56000
	ds_write_b16 v49, v55 offset:56256
	s_nop 0
	v_cvt_f16_f32_e32 v32, v50
	v_cvt_f16_f32_e32 v33, v51
	v_cvt_f16_f32_e32 v50, v52
	v_cvt_f16_f32_e32 v51, v53
	ds_write_b16 v49, v32 offset:55520
	ds_write_b16 v49, v33 offset:55776
	ds_write_b16 v49, v50 offset:56032
	ds_write_b16 v49, v51 offset:56288
	s_waitcnt lgkmcnt(0)
	s_barrier
	s_cbranch_scc0 .LBB0_219
	s_cmp_gt_i32 s26, -1
	s_cbranch_scc0 .LBB0_234
	s_mov_b32 s27, 0
	s_waitcnt vmcnt(0)
	ds_read_b128 v[0:3], v42 offset:55296
	ds_read_b128 v[4:7], v42 offset:63488
	s_lshl_b64 s[8:9], s[26:27], 15
	s_add_u32 s8, s29, s8
	s_addc_u32 s9, s44, s9
	v_lshl_add_u64 v[8:9], v[16:17], 1, s[8:9]
	s_waitcnt lgkmcnt(1)
	global_store_dwordx4 v[8:9], v[0:3], off sc1
	ds_read_b128 v[0:3], v39 offset:16384
	ds_read_b128 v[8:11], v39 offset:24576
	v_lshl_add_u64 v[12:13], v[26:27], 1, s[8:9]
	s_waitcnt lgkmcnt(2)
	global_store_dwordx4 v[12:13], v[4:7], off sc1
	s_nop 1
	v_lshl_add_u64 v[4:5], v[24:25], 1, s[8:9]
	s_waitcnt lgkmcnt(1)
	global_store_dwordx4 v[4:5], v[0:3], off sc1
	s_nop 1
	v_lshl_add_u64 v[0:1], v[28:29], 1, s[8:9]
	s_waitcnt lgkmcnt(0)
	global_store_dwordx4 v[0:1], v[8:11], off sc1

; #define LAS __attribute__((address_space(3)))
; template <int COOP>
; __global__ void __launch_bounds__(512, 2) mega(Args a) {
;     extern __shared__ __attribute__((aligned(16))) unsigned char lds_raw[];
;     LAS unsigned char* lds = (LAS unsigned char*)lds_raw;
;     const int G = gridDim.x, bx = blockIdx.x, wave0 = __builtin_amdgcn_readfirstlane((int)threadIdx.x >> 6);
	.amdhsa_kernel _Z4megaILi1EEv4Args
		.amdhsa_group_segment_fixed_size 0
		.amdhsa_private_segment_fixed_size 0
		.amdhsa_kernarg_size 368
		.amdhsa_user_sgpr_count 2
		.amdhsa_user_sgpr_dispatch_ptr 0
		.amdhsa_user_sgpr_queue_ptr 0
		.amdhsa_user_sgpr_kernarg_segment_ptr 1
		.amdhsa_user_sgpr_dispatch_id 0
		.amdhsa_user_sgpr_kernarg_preload_length 0
		.amdhsa_user_sgpr_kernarg_preload_offset 0
		.amdhsa_user_sgpr_private_segment_size 0
		.amdhsa_uses_dynamic_stack 0
		.amdhsa_enable_private_segment 0
		.amdhsa_system_sgpr_workgroup_id_x 1
		.amdhsa_system_sgpr_workgroup_id_y 0
		.amdhsa_system_sgpr_workgroup_id_z 0
		.amdhsa_system_sgpr_workgroup_info 0
		.amdhsa_system_vgpr_workitem_id 2
		.amdhsa_next_free_vgpr 254
		.amdhsa_next_free_sgpr 100
		.amdhsa_accum_offset 256
		.amdhsa_reserve_vcc 1
		.amdhsa_float_round_mode_32 0
		.amdhsa_float_round_mode_16_64 0
		.amdhsa_float_denorm_mode_32 3
		.amdhsa_float_denorm_mode_16_64 3
		.amdhsa_dx10_clamp 1
		.amdhsa_ieee_mode 1
		.amdhsa_fp16_overflow 0
		.amdhsa_tg_split 0
		.amdhsa_exception_fp_ieee_invalid_op 0
		.amdhsa_exception_fp_denorm_src 0
		.amdhsa_exception_fp_ieee_div_zero 0
		.amdhsa_exception_fp_ieee_overflow 0
		.amdhsa_exception_fp_ieee_underflow 0
		.amdhsa_exception_fp_ieee_inexact 0
		.amdhsa_exception_int_div_zero 0
	.end_amdhsa_kernel

; template <int COOP>
; __global__ void __launch_bounds__(512, 2) mega(Args a) {
amdhsa.kernels:
  - .agpr_count:     0
    .args:
      - .offset:         0
        .size:           112
        .value_kind:     by_value
      - .offset:         112
        .size:           4
        .value_kind:     hidden_block_count_x
      - .offset:         116
        .size:           4
        .value_kind:     hidden_block_count_y
      - .offset:         120
        .size:           4
        .value_kind:     hidden_block_count_z
      - .offset:         124
        .size:           2
        .value_kind:     hidden_group_size_x
      - .offset:         126
        .size:           2
        .value_kind:     hidden_group_size_y
      - .offset:         128
        .size:           2
        .value_kind:     hidden_group_size_z
      - .offset:         130
        .size:           2
        .value_kind:     hidden_remainder_x
      - .offset:         132
        .size:           2
        .value_kind:     hidden_remainder_y
      - .offset:         134
        .size:           2
        .value_kind:     hidden_remainder_z
      - .offset:         152
        .size:           8
        .value_kind:     hidden_global_offset_x
      - .offset:         160
        .size:           8
        .value_kind:     hidden_global_offset_y
      - .offset:         168
        .size:           8
        .value_kind:     hidden_global_offset_z
      - .offset:         176
        .size:           2
        .value_kind:     hidden_grid_dims
      - .offset:         200
        .size:           8
        .value_kind:     hidden_multigrid_sync_arg
      - .offset:         232
        .size:           4
        .value_kind:     hidden_dynamic_lds_size
    .group_segment_fixed_size: 0
    .kernarg_segment_align: 8
    .kernarg_segment_size: 368
    .language:       OpenCL C
    .language_version:
      - 2
      - 0
    .max_flat_workgroup_size: 512
    .name:           _Z4megaILi1EEv4Args
    .private_segment_fixed_size: 0
    .sgpr_count:     106
    .sgpr_spill_count: 0
    .symbol:         _Z4megaILi1EEv4Args.kd
    .uniform_work_group_size: 1
    .uses_dynamic_stack: false
    .vgpr_count:     254
    .vgpr_spill_count: 0
    .wavefront_size: 64
